# rwkv_prep: next iteration's r/k/a rows touched (1 dword per lane) behind the iteration's last loads so the next iteration's loads hit L2; on top of v94
# speedup vs baseline: 1.0047x; 1.0047x over previous
.LBB0_514:
	v_and_b32_e32 v0, 0x1fff, v64
	v_cmp_ne_u32_e32 vcc, s18, v0
	v_lshl_add_u64 v[20:21], s[66:67], 0, v[76:77]
	v_mov_b32_e32 v1, s49
	v_cndmask_b32_e64 v0, 0, 1, vcc
	global_load_dwordx4 v[44:47], v[20:21], off
	global_load_dwordx4 v[40:43], v[20:21], off offset:16
	v_lshl_add_u64 v[0:1], v[64:65], 0, v[0:1]
	s_mov_b64 s[8:9], 0x2000000
	v_lshlrev_b64 v[0:1], 11, v[0:1]
	v_lshl_add_u64 v[2:3], v[20:21], 0, s[8:9]
	v_lshl_add_u64 v[0:1], v[72:73], 0, v[0:1]
	global_load_dwordx4 v[12:15], v[2:3], off offset:16
	global_load_dwordx4 v[52:55], v[0:1], off
	global_load_dwordx4 v[48:51], v[0:1], off offset:16
	global_load_dwordx4 v[16:19], v[66:67], off
	global_load_dwordx4 v[8:11], v[66:67], off offset:16
	global_load_dwordx4 v[4:7], v[66:67], off offset:32
	s_nop 0
	global_load_dwordx4 v[0:3], v[66:67], off offset:48
	s_brev_b32 s0, 64
	v_add_co_u32_e32 v20, vcc, s0, v20
	v_lshl_add_u64 v[24:25], s[66:67], 0, v[78:79]
	s_nop 0
	v_addc_co_u32_e32 v21, vcc, 0, v21, vcc
	global_load_dwordx4 v[20:23], v[20:21], off
	v_lshl_add_u64 v[26:27], v[24:25], 0, s[8:9]
	v_add_co_u32_e32 v24, vcc, s0, v24
	global_load_dwordx4 v[28:31], v[26:27], off offset:16
	s_nop 0
	v_addc_co_u32_e32 v25, vcc, 0, v25, vcc
	global_load_dwordx4 v[24:27], v[24:25], off
	s_nop 0
	global_load_dwordx4 v[36:39], v[68:69], off
	global_load_dwordx4 v[32:35], v[68:69], off offset:16
	global_load_dwordx4 v[56:59], v[68:69], off offset:32
	global_load_dwordx4 v[60:63], v[68:69], off offset:48
	s_waitcnt vmcnt(15)
	v_lshlrev_b32_e32 v121, 16, v47
	v_and_b32_e32 v146, 0xffff0000, v47
	v_lshlrev_b32_e32 v125, 16, v46
	s_waitcnt vmcnt(12)
	v_and_b32_e32 v47, 0xffff0000, v52
	v_and_b32_e32 v123, 0xffff0000, v46
	v_lshlrev_b32_e32 v46, 16, v52
	s_waitcnt vmcnt(10)
	v_mul_f32_e32 v92, v17, v47
	v_lshlrev_b32_e32 v52, 16, v53
	v_mul_f32_e32 v46, v16, v46
	v_mul_f32_e32 v47, v92, v92
	v_and_b32_e32 v53, 0xffff0000, v53
	v_mul_f32_e32 v93, v18, v52
	v_fmac_f32_e32 v47, v46, v46
	v_lshlrev_b32_e32 v80, 16, v54
	v_mul_f32_e32 v94, v19, v53
	v_fmac_f32_e32 v47, v93, v93
	v_and_b32_e32 v54, 0xffff0000, v54
	s_waitcnt vmcnt(9)
	v_mul_f32_e32 v95, v8, v80
	v_fmac_f32_e32 v47, v94, v94
	v_lshlrev_b32_e32 v82, 16, v55
	v_mul_f32_e32 v96, v9, v54
	v_fmac_f32_e32 v47, v95, v95
	v_and_b32_e32 v55, 0xffff0000, v55
	v_mul_f32_e32 v97, v10, v82
	v_fmac_f32_e32 v47, v96, v96
	v_lshlrev_b32_e32 v83, 16, v48
	v_mul_f32_e32 v98, v11, v55
	v_fmac_f32_e32 v47, v97, v97
	v_lshlrev_b32_e32 v119, 16, v40
	v_and_b32_e32 v117, 0xffff0000, v40
	v_lshlrev_b32_e32 v115, 16, v41
	v_and_b32_e32 v111, 0xffff0000, v41
	v_and_b32_e32 v48, 0xffff0000, v48
	v_lshlrev_b32_e32 v40, 16, v49
	v_and_b32_e32 v41, 0xffff0000, v49
	s_waitcnt vmcnt(8)
	v_mul_f32_e32 v100, v4, v83
	v_fmac_f32_e32 v47, v98, v98
	v_mul_f32_e32 v101, v5, v48
	v_pk_mul_f32 v[90:91], v[6:7], v[40:41]
	v_fmac_f32_e32 v47, v100, v100
	v_lshlrev_b32_e32 v109, 16, v42
	v_and_b32_e32 v105, 0xffff0000, v42
	v_lshlrev_b32_e32 v99, 16, v43
	v_and_b32_e32 v85, 0xffff0000, v43
	v_lshlrev_b32_e32 v42, 16, v50
	v_and_b32_e32 v43, 0xffff0000, v50
	v_pk_mul_f32 v[40:41], v[90:91], v[90:91]
	v_fmac_f32_e32 v47, v101, v101
	s_waitcnt vmcnt(7)
	v_pk_mul_f32 v[88:89], v[0:1], v[42:43]
	v_add_f32_e32 v40, v47, v40
	v_lshlrev_b32_e32 v145, 16, v44
	v_and_b32_e32 v144, 0xffff0000, v44
	v_lshlrev_b32_e32 v143, 16, v45
	v_and_b32_e32 v142, 0xffff0000, v45
	v_lshlrev_b32_e32 v44, 16, v51
	v_and_b32_e32 v45, 0xffff0000, v51
	v_pk_mul_f32 v[42:43], v[88:89], v[88:89]
	v_add_f32_e32 v40, v40, v41
	v_pk_mul_f32 v[86:87], v[2:3], v[44:45]
	v_add_f32_e32 v40, v40, v42
	v_pk_mul_f32 v[44:45], v[86:87], v[86:87]
	v_add_f32_e32 v40, v40, v43
	v_add_f32_e32 v40, v40, v44
	v_add_f32_e32 v40, v40, v45
	s_waitcnt vmcnt(4)
	v_lshlrev_b32_e32 v162, 16, v24
	v_lshlrev_b32_e32 v163, 16, v20
	v_add_f32_dpp v40, v40, v40 quad_perm:[1,0,3,2] row_mask:0xf bank_mask:0xf bound_ctrl:1
	v_and_b32_e32 v165, 0xffff0000, v20
	v_and_b32_e32 v164, 0xffff0000, v24
	v_add_f32_dpp v40, v40, v40 quad_perm:[2,3,0,1] row_mask:0xf bank_mask:0xf bound_ctrl:1
	v_max_f32_e32 v40, 0x179abe15, v40
	v_rsq_f32_e32 v147, v40
	v_lshlrev_b32_e32 v166, 16, v25
	v_mov_b32_e32 v190, v17
	v_mov_b32_e32 v212, v163
	v_mul_f32_e32 v84, v46, v147
	global_load_dwordx4 v[40:43], v[70:71], off offset:48
	global_load_dwordx4 v[44:47], v[70:71], off offset:32
	global_load_dwordx4 v[48:51], v[70:71], off offset:16
	global_load_dwordx4 v[52:55], v[70:71], off
	s_mov_b64 s[100:101], 0x2000000
	v_lshl_add_u64 v[214:215], v[76:77], 0, s[24:25]
	v_lshl_add_u64 v[216:217], v[78:79], 0, s[24:25]
	v_lshl_add_u64 v[214:215], v[214:215], 0, s[66:67]
	v_lshl_add_u64 v[216:217], v[216:217], 0, s[66:67]
	v_lshl_add_u64 v[218:219], v[214:215], 0, s[100:101]
	v_lshl_add_u64 v[216:217], v[216:217], 0, s[100:101]
	global_load_dword v220, v[214:215], off
	global_load_dword v221, v[218:219], off
	global_load_dword v222, v[218:219], off offset:2048
	global_load_dword v223, v[216:217], off
	v_mul_f32_e32 v110, v98, v147
	v_mul_f32_e32 v98, v90, v147
	v_mul_f32_e32 v90, v91, v147
	v_add_f32_e32 v91, -1.0, v162
	v_mov_b32_e32 v17, v91
	s_waitcnt vmcnt(11)
	v_mov_b32_e32 v213, v36
	v_mul_f32_e32 v114, v92, v147
	v_mul_f32_e32 v116, v93, v147
	v_mul_f32_e32 v124, v97, v147
	v_lshlrev_b32_e32 v103, 16, v14
	v_and_b32_e32 v97, 0xffff0000, v14
	v_lshlrev_b32_e32 v93, 16, v15
	v_lshlrev_b32_e32 v92, 16, v31
	v_and_b32_e32 v15, 0xffff0000, v15
	v_and_b32_e32 v14, 0xffff0000, v31
	v_lshlrev_b32_e32 v167, 16, v21
	v_add_f32_e32 v191, -1.0, v164
	v_add_f32_e32 v176, -1.0, v166
	v_mov_b32_e32 v208, v165
	v_mov_b32_e32 v209, v37
	v_pk_mul_f32 v[36:37], v[16:17], v[212:213]
	v_mul_f32_e32 v118, v94, v147
	v_mul_f32_e32 v120, v95, v147
	v_mul_f32_e32 v122, v96, v147
	v_lshlrev_b32_e32 v102, 16, v30
	v_and_b32_e32 v96, 0xffff0000, v30
	v_add_f32_e32 v31, -1.0, v14
	v_mov_b32_e32 v30, v3
	v_mov_b32_e32 v94, v15
	s_waitcnt vmcnt(8)
	v_mov_b32_e32 v95, v63
	v_add_f32_e32 v3, -1.0, v92
	v_mov_b32_e32 v126, v93
	v_mov_b32_e32 v127, v62
	v_and_b32_e32 v21, 0xffff0000, v21
	v_and_b32_e32 v20, 0xffff0000, v25
	v_lshlrev_b32_e32 v24, 16, v26
	v_mov_b32_e32 v192, v19
	v_mov_b32_e32 v19, v176
	v_mov_b32_e32 v206, v167
	v_mov_b32_e32 v207, v38
	v_pk_mul_f32 v[210:211], v[190:191], v[208:209]
	v_mul_f32_e32 v91, v36, v36
	v_lshlrev_b32_e32 v80, 16, v29
	v_mul_f32_e32 v108, v100, v147
	v_mul_f32_e32 v104, v101, v147
	v_pk_mul_f32 v[100:101], v[30:31], v[94:95]
	v_pk_mul_f32 v[62:63], v[2:3], v[126:127]
	v_lshlrev_b32_e32 v25, 16, v22
	v_add_f32_e32 v193, -1.0, v20
	v_add_f32_e32 v178, -1.0, v24
	v_mov_b32_e32 v202, v21
	v_mov_b32_e32 v203, v39
	v_pk_mul_f32 v[38:39], v[18:19], v[206:207]
	v_fmac_f32_e32 v91, v210, v210
	v_lshlrev_b32_e32 v81, 16, v13
	v_and_b32_e32 v107, 0xffff0000, v13
	v_and_b32_e32 v106, 0xffff0000, v29
	v_add_f32_e32 v13, -1.0, v80
	v_add_f32_e32 v29, -1.0, v102
	v_mov_b32_e32 v132, v62
	v_mov_b32_e32 v133, v100
	v_and_b32_e32 v169, 0xffff0000, v22
	v_and_b32_e32 v168, 0xffff0000, v26
	v_mov_b32_e32 v194, v9
	v_mov_b32_e32 v9, v178
	v_mov_b32_e32 v200, v25
	v_mov_b32_e32 v201, v32
	v_pk_mul_f32 v[204:205], v[192:193], v[202:203]
	v_fmac_f32_e32 v91, v38, v38
	v_and_b32_e32 v83, 0xffff0000, v12
	v_and_b32_e32 v82, 0xffff0000, v28
	v_add_f32_e32 v129, -1.0, v96
	v_pk_mul_f32 v[148:149], v[132:133], v[132:133]
	v_mov_b32_e32 v128, v1
	v_mov_b32_e32 v132, v97
	v_mov_b32_e32 v133, v61
	v_mov_b32_e32 v1, v29
	v_mov_b32_e32 v136, v103
	v_mov_b32_e32 v137, v60
	v_mov_b32_e32 v130, v7
	v_mov_b32_e32 v7, v13
	v_lshlrev_b32_e32 v13, 16, v12
	v_lshlrev_b32_e32 v12, 16, v28
	v_lshlrev_b32_e32 v171, 16, v23
	v_lshlrev_b32_e32 v170, 16, v27
	v_add_f32_e32 v195, -1.0, v168
	v_mov_b32_e32 v196, v169
	v_mov_b32_e32 v197, v33
	v_pk_mul_f32 v[32:33], v[8:9], v[200:201]
	v_fmac_f32_e32 v91, v204, v204
	v_add_f32_e32 v113, -1.0, v82
	v_pk_mul_f32 v[134:135], v[128:129], v[132:133]
	v_pk_mul_f32 v[60:61], v[0:1], v[136:137]
	v_mov_b32_e32 v112, v5
	v_mov_b32_e32 v156, v83
	v_mov_b32_e32 v157, v57
	v_add_f32_e32 v5, -1.0, v12
	v_mov_b32_e32 v28, v13
	v_mov_b32_e32 v29, v56
	v_add_f32_e32 v173, -1.0, v170
	v_mov_b32_e32 v172, v10
	v_mov_b32_e32 v174, v171
	v_mov_b32_e32 v175, v34
	v_and_b32_e32 v23, 0xffff0000, v23
	v_and_b32_e32 v22, 0xffff0000, v27
	v_pk_mul_f32 v[198:199], v[194:195], v[196:197]
	v_fmac_f32_e32 v91, v32, v32
	v_mov_b32_e32 v138, v60
	v_mov_b32_e32 v139, v134
	v_pk_mul_f32 v[158:159], v[112:113], v[156:157]
	v_pk_mul_f32 v[56:57], v[4:5], v[28:29]
	v_pk_mul_f32 v[188:189], v[172:173], v[174:175]
	v_add_f32_e32 v27, -1.0, v22
	v_mov_b32_e32 v26, v11
	v_mov_b32_e32 v34, v23
	v_fmac_f32_e32 v91, v198, v198
	v_add_f32_e32 v131, -1.0, v106
	v_pk_mul_f32 v[150:151], v[138:139], v[138:139]
	v_mov_b32_e32 v138, v107
	v_mov_b32_e32 v139, v59
	v_mov_b32_e32 v152, v81
	v_mov_b32_e32 v153, v58
	v_mov_b32_e32 v160, v56
	v_mov_b32_e32 v161, v158
	v_pk_mul_f32 v[10:11], v[26:27], v[34:35]
	v_fmac_f32_e32 v91, v188, v188
	v_pk_mul_f32 v[140:141], v[130:131], v[138:139]
	v_pk_mul_f32 v[58:59], v[6:7], v[152:153]
	v_pk_mul_f32 v[160:161], v[160:161], v[160:161]
	v_fmac_f32_e32 v91, v10, v10
	v_mov_b32_e32 v154, v58
	v_mov_b32_e32 v155, v140
	v_add_f32_e32 v91, v91, v160
	v_pk_mul_f32 v[154:155], v[154:155], v[154:155]
	v_add_f32_e32 v91, v91, v161
	v_add_f32_e32 v91, v91, v154
	v_add_f32_e32 v91, v91, v155
	v_add_f32_e32 v91, v91, v150
	v_add_f32_e32 v91, v91, v151
	v_add_f32_e32 v91, v91, v148
	v_add_f32_e32 v91, v91, v149
	v_pk_fma_f32 v[26:27], v[26:27], v[34:35], s[26:27]
	v_pk_fma_f32 v[16:17], v[16:17], v[212:213], s[26:27]
	v_add_f32_dpp v91, v91, v91 quad_perm:[1,0,3,2] row_mask:0xf bank_mask:0xf bound_ctrl:1
	v_pk_fma_f32 v[18:19], v[18:19], v[206:207], s[26:27]
	v_pk_fma_f32 v[34:35], v[192:193], v[202:203], s[26:27]
	v_add_f32_dpp v91, v91, v91 quad_perm:[2,3,0,1] row_mask:0xf bank_mask:0xf bound_ctrl:1
	v_max_f32_e32 v91, 0x179abe15, v91
	v_rsq_f32_e32 v178, v91
	v_pk_fma_f32 v[8:9], v[8:9], v[200:201], s[26:27]
	v_pk_fma_f32 v[4:5], v[4:5], v[28:29], s[26:27]
	v_mul_f32_e32 v150, v87, v147
	v_pk_mul_f32 v[10:11], v[10:11], v[178:179]
	v_pk_fma_f32 v[6:7], v[6:7], v[152:153], s[26:27]
	v_mov_b32_e32 v11, v27
	v_pk_mul_f32 v[10:11], v[10:11], v[22:23]
	v_pk_mul_f32 v[22:23], v[36:37], v[178:179]
	v_pk_fma_f32 v[26:27], v[190:191], v[208:209], s[26:27]
	v_mov_b32_e32 v23, v17
	v_pk_mul_f32 v[16:17], v[22:23], v[162:163]
	v_mul_f32_e32 v87, v11, v146
	v_mul_f32_e32 v22, v17, v145
	s_waitcnt vmcnt(4)
	v_fma_f32 v36, v52, v22, 0
	v_pk_mul_f32 v[22:23], v[210:211], v[178:179]
	v_pk_fma_f32 v[0:1], v[0:1], v[136:137], s[26:27]
	v_mov_b32_e32 v23, v27
	v_pk_mul_f32 v[22:23], v[22:23], v[164:165]
	v_mul_f32_e32 v88, v88, v147
	v_mul_f32_e32 v26, v23, v144
	v_fmac_f32_e32 v36, v53, v26
	v_pk_mul_f32 v[26:27], v[38:39], v[178:179]
	v_mul_f32_e32 v148, v89, v147
	v_mov_b32_e32 v27, v19
	v_pk_mul_f32 v[18:19], v[26:27], v[166:167]
	v_pk_fma_f32 v[2:3], v[2:3], v[126:127], s[26:27]
	v_mul_f32_e32 v26, v19, v143
	v_fmac_f32_e32 v36, v54, v26
	v_pk_mul_f32 v[26:27], v[204:205], v[178:179]
	v_mul_f32_e32 v86, v86, v147
	v_mov_b32_e32 v27, v35
	v_pk_mul_f32 v[20:21], v[26:27], v[20:21]
	s_nop 0
	v_mul_f32_e32 v26, v21, v142
	v_fmac_f32_e32 v36, v55, v26
	v_pk_mul_f32 v[26:27], v[32:33], v[178:179]
	v_pk_fma_f32 v[32:33], v[172:173], v[174:175], s[26:27]
	v_mov_b32_e32 v27, v9
	v_pk_mul_f32 v[8:9], v[26:27], v[24:25]
	v_pk_fma_f32 v[26:27], v[194:195], v[196:197], s[26:27]
	v_mul_f32_e32 v24, v9, v125
	v_fmac_f32_e32 v36, v48, v24
	v_pk_mul_f32 v[24:25], v[198:199], v[178:179]
	s_nop 0
	v_mov_b32_e32 v25, v27
	v_pk_mul_f32 v[24:25], v[24:25], v[168:169]
	s_nop 0
	v_mul_f32_e32 v26, v25, v123
	v_fmac_f32_e32 v36, v49, v26
	v_pk_mul_f32 v[26:27], v[188:189], v[178:179]
	s_nop 0
	v_mov_b32_e32 v27, v33
	v_pk_mul_f32 v[26:27], v[26:27], v[170:171]
	s_nop 0
	v_mul_f32_e32 v32, v27, v121
	v_fmac_f32_e32 v36, v50, v32
	v_pk_mul_f32 v[32:33], v[56:57], v[178:179]
	v_fmac_f32_e32 v36, v51, v87
	v_mov_b32_e32 v33, v5
	v_pk_mul_f32 v[4:5], v[32:33], v[12:13]
	s_nop 0
	v_mul_f32_e32 v12, v5, v119
	v_fmac_f32_e32 v36, v44, v12
	v_pk_fma_f32 v[12:13], v[16:17], v[84:85], 0 op_sel_hi:[1,0,0]
	s_nop 0
	v_pk_fma_f32 v[12:13], v[114:115], v[22:23], v[12:13] op_sel_hi:[0,1,1]
	v_pk_fma_f32 v[12:13], v[116:117], v[18:19], v[12:13] op_sel_hi:[0,1,1]
	v_pk_fma_f32 v[12:13], v[118:119], v[20:21], v[12:13] op_sel_hi:[0,1,1]
	v_pk_fma_f32 v[8:9], v[120:121], v[8:9], v[12:13] op_sel_hi:[0,1,1]
	v_pk_fma_f32 v[8:9], v[122:123], v[24:25], v[8:9] op_sel_hi:[0,1,1]
	v_pk_fma_f32 v[8:9], v[124:125], v[26:27], v[8:9] op_sel_hi:[0,1,1]
	v_pk_fma_f32 v[8:9], v[110:111], v[10:11], v[8:9] op_sel_hi:[0,1,1]
	v_pk_fma_f32 v[4:5], v[108:109], v[4:5], v[8:9] op_sel_hi:[0,1,1]
	v_pk_mul_f32 v[8:9], v[158:159], v[178:179]
	v_pk_fma_f32 v[10:11], v[112:113], v[156:157], s[26:27]
	s_nop 0
	v_mov_b32_e32 v9, v11
	v_pk_mul_f32 v[8:9], v[8:9], v[82:83]
	s_nop 0
	v_pk_fma_f32 v[4:5], v[104:105], v[8:9], v[4:5] op_sel_hi:[0,1,1]
	v_mul_f32_e32 v8, v9, v117
	v_fmac_f32_e32 v36, v45, v8
	v_pk_mul_f32 v[8:9], v[58:59], v[178:179]
	s_nop 0
	v_mov_b32_e32 v9, v7
	v_pk_mul_f32 v[6:7], v[8:9], v[80:81]
	v_pk_fma_f32 v[8:9], v[130:131], v[138:139], s[26:27]
	v_pk_fma_f32 v[4:5], v[98:99], v[6:7], v[4:5] op_sel_hi:[0,1,1]
	v_mul_f32_e32 v6, v7, v115
	v_fmac_f32_e32 v36, v46, v6
	v_pk_mul_f32 v[6:7], v[140:141], v[178:179]
	s_nop 0
	v_mov_b32_e32 v7, v9
	v_pk_mul_f32 v[6:7], v[6:7], v[106:107]
	s_nop 0
	v_pk_fma_f32 v[4:5], v[90:91], v[6:7], v[4:5] op_sel_hi:[0,1,1]
	v_mul_f32_e32 v6, v7, v111
	v_fmac_f32_e32 v36, v47, v6
	v_pk_mul_f32 v[6:7], v[60:61], v[178:179]
	s_nop 0
	v_mov_b32_e32 v7, v1
	v_pk_mul_f32 v[0:1], v[6:7], v[102:103]
	v_pk_fma_f32 v[6:7], v[128:129], v[132:133], s[26:27]
	v_pk_fma_f32 v[4:5], v[88:89], v[0:1], v[4:5] op_sel_hi:[0,1,1]
	v_mul_f32_e32 v0, v1, v109
	v_fmac_f32_e32 v36, v40, v0
	v_pk_mul_f32 v[0:1], v[134:135], v[178:179]
	s_nop 0
	v_mov_b32_e32 v1, v7
	v_pk_mul_f32 v[0:1], v[0:1], v[96:97]
	s_nop 0
	v_pk_fma_f32 v[4:5], v[148:149], v[0:1], v[4:5] op_sel_hi:[0,1,1]
	v_mul_f32_e32 v0, v1, v105
	v_fmac_f32_e32 v36, v41, v0
	v_pk_mul_f32 v[0:1], v[62:63], v[178:179]
	s_nop 0
	v_mov_b32_e32 v1, v3
	v_pk_mul_f32 v[0:1], v[0:1], v[92:93]
	s_nop 0
	v_pk_fma_f32 v[2:3], v[86:87], v[0:1], v[4:5] op_sel_hi:[0,1,1]
	v_mul_f32_e32 v0, v1, v99
	v_fmac_f32_e32 v36, v42, v0
	v_pk_mul_f32 v[0:1], v[100:101], v[178:179]
	v_pk_fma_f32 v[4:5], v[30:31], v[94:95], s[26:27]
	s_nop 0
	v_mov_b32_e32 v1, v5
	v_pk_mul_f32 v[0:1], v[0:1], v[14:15]
	v_mov_b32_e32 v5, 0
	v_pk_fma_f32 v[2:3], v[150:151], v[0:1], v[2:3] op_sel_hi:[0,1,1]
	v_mul_f32_e32 v0, v1, v85
	v_fmac_f32_e32 v36, v43, v0
	v_mov_b32_e32 v0, v177
	v_mov_b32_e32 v1, v177
	v_add_f32_dpp v4, v36, v36 quad_perm:[1,0,3,2] row_mask:0xf bank_mask:0xf bound_ctrl:1
	v_mov_b32_dpp v0, v2 quad_perm:[1,0,3,2] row_mask:0xf bank_mask:0xf
	v_mov_b32_dpp v1, v3 quad_perm:[1,0,3,2] row_mask:0xf bank_mask:0xf
	v_pk_add_f32 v[0:1], v[2:3], v[0:1]
	v_mov_b32_e32 v2, 0
	v_mov_b32_e32 v3, 0
	v_mov_b32_dpp v5, v4 quad_perm:[2,3,0,1] row_mask:0xf bank_mask:0xf
	v_mov_b32_dpp v2, v0 quad_perm:[2,3,0,1] row_mask:0xf bank_mask:0xf
	v_mov_b32_dpp v3, v1 quad_perm:[2,3,0,1] row_mask:0xf bank_mask:0xf
	s_and_saveexec_b64 s[0:1], s[2:3]
	s_cbranch_execz .LBB0_513
	v_pk_add_f32 v[8:9], v[0:1], v[2:3]
	v_lshl_add_u64 v[6:7], s[66:67], 0, v[74:75]
	v_add_f32_e32 v3, v4, v5
	v_mov_b32_e32 v0, v178
	v_mov_b32_e32 v1, v8
	v_mov_b32_e32 v2, v9
	global_store_dwordx4 v[6:7], v[0:3], off
	s_branch .LBB0_513
